# P14 K loop rewritten as super-phase (two MFMA blocks per barrier pair, 8 barriers per 2 K-tiles), prologue wait vmcnt(2)
# speedup vs baseline: 1.0006x; 1.0006x over previous
.LBB0_1696:
	s_add_u32 s26, s14, 0x1200000
	s_addc_u32 s27, s15, 0
	s_add_u32 s28, s14, 0x8e00000
	s_addc_u32 s29, s15, 0
	s_add_u32 s33, s14, 0x6e00000
	s_addc_u32 s64, s15, 0
	s_add_u32 s34, s12, 0x2000000
	s_addc_u32 s35, s13, 0
	s_add_u32 s36, s14, 0xce00000
	s_mov_b64 s[38:39], 0x80
	s_addc_u32 s37, s15, 0
	v_lshl_add_u64 v[10:11], v[2:3], 0, s[38:39]
	s_add_i32 m0, s6, 0x18000
	s_mov_b64 s[40:41], 0x20080
	s_waitcnt vmcnt(2)
	s_barrier
	global_load_lds_dwordx4 v[10:11], off
	v_lshl_add_u64 v[10:11], v[2:3], 0, s[40:41]
	s_add_i32 m0, s6, 0x1a000
	s_add_i32 s65, s6, 0x8000
	global_load_lds_dwordx4 v[10:11], off
	v_lshl_add_u64 v[10:11], v[4:5], 0, s[38:39]
	s_mov_b32 m0, s65
	s_add_i32 s66, s6, 0xa000
	global_load_lds_dwordx4 v[10:11], off
	v_lshl_add_u64 v[4:5], v[4:5], 0, s[40:41]
	s_mov_b32 m0, s66
	s_mov_b64 s[42:43], 0x40080
	global_load_lds_dwordx4 v[4:5], off
	v_lshl_add_u64 v[4:5], v[2:3], 0, s[42:43]
	s_add_i32 m0, s6, 0x1c000
	s_mov_b64 s[44:45], 0x60080
	global_load_lds_dwordx4 v[4:5], off
	v_lshl_add_u64 v[2:3], v[2:3], 0, s[44:45]
	s_add_i32 m0, s6, 0x1e000
	v_bfe_u32 v211, v6, 4, 2
	global_load_lds_dwordx4 v[2:3], off
	s_lshl_b32 s1, s1, 5
	v_and_b32_e32 v210, 15, v6
	v_lshlrev_b32_e32 v2, 4, v211
	v_lshlrev_b32_e32 v3, 2, v6
	s_and_b32 s68, s1, 0x60
	s_lshl_b32 s67, s8, 6
	v_lshl_or_b32 v2, v210, 6, v2
	s_lshl_b32 s8, s8, 13
	v_and_b32_e32 v3, 32, v3
	s_lshl_b32 s1, s68, 7
	v_bitop3_b32 v4, v2, s8, v3 bitop3:0xde
	v_bitop3_b32 v212, v2, s1, v3 bitop3:0xde
	v_lshlrev_b32_e32 v2, 14, v7
	s_cmpk_lt_u32 s0, 0x100
	v_and_b32_e32 v2, 0xffff8000, v2
	s_waitcnt vmcnt(6)
	s_cselect_b64 s[46:47], -1, 0
	s_add_u32 s71, s14, 0x2106000
	v_lshl_add_u32 v2, v8, 11, v2
	v_and_b32_e32 v3, 1, v7
	s_addc_u32 s72, s15, 0
	v_lshl_or_b32 v2, v3, 6, v2
	s_add_i32 s73, 0, 0x10000
	s_add_i32 s74, 0, 0x14000
	s_mov_b32 s69, 0x18000
	s_mov_b32 s70, 0x8000
	v_lshl_add_u32 v198, v9, 1, v2
	v_mov_b32_e32 v199, v197
	v_add_u32_e32 v213, s73, v212
	v_add_u32_e32 v214, 0, v4
	v_add_u32_e32 v215, s74, v212
	s_mov_b32 s75, 0x40000
	s_mov_b32 s76, 0x48000
	s_mov_b32 s77, 0x50000
	s_mov_b32 s78, 0x58000
	s_mov_b32 s79, 0x42a00000
	s_mov_b32 s85, 0
	s_mov_b32 s81, 0
	s_barrier
	s_branch .LBB0_1699

.LBB0_1706:
	ds_read_b128 v[130:133], v213
	ds_read_b128 v[134:137], v213 offset:1024
	ds_read_b128 v[138:141], v213 offset:2048
	ds_read_b128 v[142:145], v213 offset:3072
	ds_read_b128 v[178:181], v215
	ds_read_b128 v[182:185], v215 offset:1024
	ds_read_b128 v[186:189], v215 offset:2048
	ds_read_b128 v[190:193], v215 offset:3072
	s_add_u32 s0, s60, 0xfffc0080
	s_addc_u32 s1, s61, -1
	s_cmp_eq_u32 s86, 12
	s_cselect_b32 s1, s9, s1
	s_cselect_b32 s0, s8, s0
	s_cselect_b32 s31, s59, s63
	s_cselect_b32 s30, s58, s62
	v_lshl_add_u64 v[252:253], s[60:61], 0, v[198:199]
	s_add_i32 m0, s6, 0xc000
	ds_read_b128 v[146:149], v214
	ds_read_b128 v[150:153], v214 offset:1024
	ds_read_b128 v[154:157], v214 offset:2048
	ds_read_b128 v[158:161], v214 offset:3072
	ds_read_b128 v[162:165], v214 offset:4096
	ds_read_b128 v[166:169], v214 offset:5120
	ds_read_b128 v[170:173], v214 offset:6144
	ds_read_b128 v[174:177], v214 offset:7168
	global_load_lds_dwordx4 v[252:253], off
	v_lshl_add_u64 v[252:253], v[252:253], 0, s[10:11]
	s_add_i32 m0, s6, 0xe000
	s_nop 0
	global_load_lds_dwordx4 v[252:253], off
	s_waitcnt vmcnt(8)
	s_waitcnt lgkmcnt(0)
	s_barrier
	s_setprio 1
	v_mfma_f32_16x16x32_bf16 v[126:129], v[130:133], v[146:149], v[126:129]
	v_mfma_f32_16x16x32_bf16 v[122:125], v[138:141], v[146:149], v[122:125]
	v_mfma_f32_16x16x32_bf16 v[118:121], v[130:133], v[154:157], v[118:121]
	v_mfma_f32_16x16x32_bf16 v[114:117], v[138:141], v[154:157], v[114:117]
	v_mfma_f32_16x16x32_bf16 v[110:113], v[130:133], v[162:165], v[110:113]
	v_mfma_f32_16x16x32_bf16 v[106:109], v[138:141], v[162:165], v[106:109]
	v_mfma_f32_16x16x32_bf16 v[102:105], v[130:133], v[170:173], v[102:105]
	v_mfma_f32_16x16x32_bf16 v[98:101], v[138:141], v[170:173], v[98:101]
	v_mfma_f32_16x16x32_bf16 v[126:129], v[134:137], v[150:153], v[126:129]
	v_mfma_f32_16x16x32_bf16 v[122:125], v[142:145], v[150:153], v[122:125]
	v_mfma_f32_16x16x32_bf16 v[118:121], v[134:137], v[158:161], v[118:121]
	v_mfma_f32_16x16x32_bf16 v[114:117], v[142:145], v[158:161], v[114:117]
	v_mfma_f32_16x16x32_bf16 v[110:113], v[134:137], v[166:169], v[110:113]
	v_mfma_f32_16x16x32_bf16 v[106:109], v[142:145], v[166:169], v[106:109]
	v_mfma_f32_16x16x32_bf16 v[102:105], v[134:137], v[174:177], v[102:105]
	v_mfma_f32_16x16x32_bf16 v[98:101], v[142:145], v[174:177], v[98:101]
	v_mfma_f32_16x16x32_bf16 v[62:65], v[178:181], v[146:149], v[62:65]
	v_mfma_f32_16x16x32_bf16 v[58:61], v[186:189], v[146:149], v[58:61]
	v_mfma_f32_16x16x32_bf16 v[54:57], v[178:181], v[154:157], v[54:57]
	v_mfma_f32_16x16x32_bf16 v[50:53], v[186:189], v[154:157], v[50:53]
	v_mfma_f32_16x16x32_bf16 v[46:49], v[178:181], v[162:165], v[46:49]
	v_mfma_f32_16x16x32_bf16 v[42:45], v[186:189], v[162:165], v[42:45]
	v_mfma_f32_16x16x32_bf16 v[38:41], v[178:181], v[170:173], v[38:41]
	v_mfma_f32_16x16x32_bf16 v[34:37], v[186:189], v[170:173], v[34:37]
	v_mfma_f32_16x16x32_bf16 v[62:65], v[182:185], v[150:153], v[62:65]
	v_mfma_f32_16x16x32_bf16 v[58:61], v[190:193], v[150:153], v[58:61]
	v_mfma_f32_16x16x32_bf16 v[54:57], v[182:185], v[158:161], v[54:57]
	v_mfma_f32_16x16x32_bf16 v[50:53], v[190:193], v[158:161], v[50:53]
	v_mfma_f32_16x16x32_bf16 v[46:49], v[182:185], v[166:169], v[46:49]
	v_mfma_f32_16x16x32_bf16 v[42:45], v[190:193], v[166:169], v[42:45]
	v_mfma_f32_16x16x32_bf16 v[38:41], v[182:185], v[174:177], v[38:41]
	v_mfma_f32_16x16x32_bf16 v[34:37], v[190:193], v[174:177], v[34:37]
	s_setprio 0
	s_barrier
	ds_read_b128 v[146:149], v214 offset:16384
	ds_read_b128 v[150:153], v214 offset:17408
	ds_read_b128 v[154:157], v214 offset:18432
	ds_read_b128 v[158:161], v214 offset:19456
	ds_read_b128 v[162:165], v214 offset:20480
	ds_read_b128 v[166:169], v214 offset:21504
	ds_read_b128 v[170:173], v214 offset:22528
	ds_read_b128 v[174:177], v214 offset:23552
	v_lshl_add_u64 v[202:203], s[0:1], 0, v[194:195]
	v_lshl_add_u64 v[200:201], s[30:31], 0, v[196:197]
	s_add_i32 s30, s73, s5
	s_mov_b32 m0, s30
	s_nop 0
	global_load_lds_dwordx4 v[200:201], off
	v_lshl_add_u64 v[204:205], v[200:201], 0, s[10:11]
	s_add_i32 m0, s30, 0x2000
	s_nop 0
	global_load_lds_dwordx4 v[204:205], off
	s_add_i32 s0, s74, s5
	v_lshl_add_u64 v[250:251], v[200:201], 0, s[16:17]
	s_mov_b32 m0, s0
	s_nop 0
	global_load_lds_dwordx4 v[250:251], off
	v_lshl_add_u64 v[250:251], v[200:201], 0, s[18:19]
	s_add_i32 m0, s0, 0x2000
	s_nop 0
	global_load_lds_dwordx4 v[250:251], off
	s_mov_b32 m0, s6
	s_nop 0
	global_load_lds_dwordx4 v[202:203], off
	v_lshl_add_u64 v[204:205], v[202:203], 0, s[10:11]
	s_mov_b32 m0, s7
	s_nop 0
	global_load_lds_dwordx4 v[204:205], off
	s_waitcnt vmcnt(8)
	s_waitcnt lgkmcnt(0)
	s_barrier
	s_setprio 1
	v_mfma_f32_16x16x32_bf16 v[94:97], v[130:133], v[146:149], v[94:97]
	v_mfma_f32_16x16x32_bf16 v[90:93], v[138:141], v[146:149], v[90:93]
	v_mfma_f32_16x16x32_bf16 v[86:89], v[130:133], v[154:157], v[86:89]
	v_mfma_f32_16x16x32_bf16 v[82:85], v[138:141], v[154:157], v[82:85]
	v_mfma_f32_16x16x32_bf16 v[78:81], v[130:133], v[162:165], v[78:81]
	v_mfma_f32_16x16x32_bf16 v[74:77], v[138:141], v[162:165], v[74:77]
	v_mfma_f32_16x16x32_bf16 v[70:73], v[130:133], v[170:173], v[70:73]
	v_mfma_f32_16x16x32_bf16 v[66:69], v[138:141], v[170:173], v[66:69]
	v_mfma_f32_16x16x32_bf16 v[94:97], v[134:137], v[150:153], v[94:97]
	v_mfma_f32_16x16x32_bf16 v[90:93], v[142:145], v[150:153], v[90:93]
	v_mfma_f32_16x16x32_bf16 v[86:89], v[134:137], v[158:161], v[86:89]
	v_mfma_f32_16x16x32_bf16 v[82:85], v[142:145], v[158:161], v[82:85]
	v_mfma_f32_16x16x32_bf16 v[78:81], v[134:137], v[166:169], v[78:81]
	v_mfma_f32_16x16x32_bf16 v[74:77], v[142:145], v[166:169], v[74:77]
	v_mfma_f32_16x16x32_bf16 v[70:73], v[134:137], v[174:177], v[70:73]
	v_mfma_f32_16x16x32_bf16 v[66:69], v[142:145], v[174:177], v[66:69]
	v_mfma_f32_16x16x32_bf16 v[30:33], v[178:181], v[146:149], v[30:33]
	v_mfma_f32_16x16x32_bf16 v[26:29], v[186:189], v[146:149], v[26:29]
	v_mfma_f32_16x16x32_bf16 v[22:25], v[178:181], v[154:157], v[22:25]
	v_mfma_f32_16x16x32_bf16 v[18:21], v[186:189], v[154:157], v[18:21]
	v_mfma_f32_16x16x32_bf16 v[14:17], v[178:181], v[162:165], v[14:17]
	v_mfma_f32_16x16x32_bf16 v[10:13], v[186:189], v[162:165], v[10:13]
	v_mfma_f32_16x16x32_bf16 v[6:9], v[178:181], v[170:173], v[6:9]
	v_mfma_f32_16x16x32_bf16 v[2:5], v[186:189], v[170:173], v[2:5]
	v_mfma_f32_16x16x32_bf16 v[30:33], v[182:185], v[150:153], v[30:33]
	v_mfma_f32_16x16x32_bf16 v[26:29], v[190:193], v[150:153], v[26:29]
	v_mfma_f32_16x16x32_bf16 v[22:25], v[182:185], v[158:161], v[22:25]
	v_mfma_f32_16x16x32_bf16 v[18:21], v[190:193], v[158:161], v[18:21]
	v_mfma_f32_16x16x32_bf16 v[14:17], v[182:185], v[166:169], v[14:17]
	v_mfma_f32_16x16x32_bf16 v[10:13], v[190:193], v[166:169], v[10:13]
	v_mfma_f32_16x16x32_bf16 v[6:9], v[182:185], v[174:177], v[6:9]
	v_mfma_f32_16x16x32_bf16 v[2:5], v[190:193], v[174:177], v[2:5]
	s_setprio 0
	s_add_i32 s0, 0, 0x18000
	v_add_u32_e32 v142, s0, v212
	s_barrier
	s_add_i32 s1, 0, 0x1c000
	v_add_u32_e32 v190, s1, v212
	ds_read_b128 v[130:133], v142
	ds_read_b128 v[134:137], v142 offset:1024
	ds_read_b128 v[138:141], v142 offset:2048
	ds_read_b128 v[142:145], v142 offset:3072
	ds_read_b128 v[178:181], v190
	ds_read_b128 v[182:185], v190 offset:1024
	ds_read_b128 v[186:189], v190 offset:2048
	ds_read_b128 v[190:193], v190 offset:3072
	s_mov_b32 m0, s24
	v_lshl_add_u64 v[252:253], v[202:203], 0, s[16:17]
	ds_read_b128 v[146:149], v214 offset:32768
	ds_read_b128 v[150:153], v214 offset:33792
	ds_read_b128 v[154:157], v214 offset:34816
	ds_read_b128 v[158:161], v214 offset:35840
	ds_read_b128 v[162:165], v214 offset:36864
	ds_read_b128 v[166:169], v214 offset:37888
	ds_read_b128 v[170:173], v214 offset:38912
	ds_read_b128 v[174:177], v214 offset:39936
	global_load_lds_dwordx4 v[252:253], off
	v_lshl_add_u64 v[252:253], v[202:203], 0, s[18:19]
	s_mov_b32 m0, s25
	s_nop 0
	global_load_lds_dwordx4 v[252:253], off
	s_waitcnt vmcnt(8)
	s_waitcnt lgkmcnt(0)
	s_barrier
	s_setprio 1
	v_mfma_f32_16x16x32_bf16 v[126:129], v[130:133], v[146:149], v[126:129]
	v_mfma_f32_16x16x32_bf16 v[122:125], v[138:141], v[146:149], v[122:125]
	v_mfma_f32_16x16x32_bf16 v[118:121], v[130:133], v[154:157], v[118:121]
	v_mfma_f32_16x16x32_bf16 v[114:117], v[138:141], v[154:157], v[114:117]
	v_mfma_f32_16x16x32_bf16 v[110:113], v[130:133], v[162:165], v[110:113]
	v_mfma_f32_16x16x32_bf16 v[106:109], v[138:141], v[162:165], v[106:109]
	v_mfma_f32_16x16x32_bf16 v[102:105], v[130:133], v[170:173], v[102:105]
	v_mfma_f32_16x16x32_bf16 v[98:101], v[138:141], v[170:173], v[98:101]
	v_mfma_f32_16x16x32_bf16 v[126:129], v[134:137], v[150:153], v[126:129]
	v_mfma_f32_16x16x32_bf16 v[122:125], v[142:145], v[150:153], v[122:125]
	v_mfma_f32_16x16x32_bf16 v[118:121], v[134:137], v[158:161], v[118:121]
	v_mfma_f32_16x16x32_bf16 v[114:117], v[142:145], v[158:161], v[114:117]
	v_mfma_f32_16x16x32_bf16 v[110:113], v[134:137], v[166:169], v[110:113]
	v_mfma_f32_16x16x32_bf16 v[106:109], v[142:145], v[166:169], v[106:109]
	v_mfma_f32_16x16x32_bf16 v[102:105], v[134:137], v[174:177], v[102:105]
	v_mfma_f32_16x16x32_bf16 v[98:101], v[142:145], v[174:177], v[98:101]
	v_mfma_f32_16x16x32_bf16 v[62:65], v[178:181], v[146:149], v[62:65]
	v_mfma_f32_16x16x32_bf16 v[58:61], v[186:189], v[146:149], v[58:61]
	v_mfma_f32_16x16x32_bf16 v[54:57], v[178:181], v[154:157], v[54:57]
	v_mfma_f32_16x16x32_bf16 v[50:53], v[186:189], v[154:157], v[50:53]
	v_mfma_f32_16x16x32_bf16 v[46:49], v[178:181], v[162:165], v[46:49]
	v_mfma_f32_16x16x32_bf16 v[42:45], v[186:189], v[162:165], v[42:45]
	v_mfma_f32_16x16x32_bf16 v[38:41], v[178:181], v[170:173], v[38:41]
	v_mfma_f32_16x16x32_bf16 v[34:37], v[186:189], v[170:173], v[34:37]
	v_mfma_f32_16x16x32_bf16 v[62:65], v[182:185], v[150:153], v[62:65]
	v_mfma_f32_16x16x32_bf16 v[58:61], v[190:193], v[150:153], v[58:61]
	v_mfma_f32_16x16x32_bf16 v[54:57], v[182:185], v[158:161], v[54:57]
	v_mfma_f32_16x16x32_bf16 v[50:53], v[190:193], v[158:161], v[50:53]
	v_mfma_f32_16x16x32_bf16 v[46:49], v[182:185], v[166:169], v[46:49]
	v_mfma_f32_16x16x32_bf16 v[42:45], v[190:193], v[166:169], v[42:45]
	v_mfma_f32_16x16x32_bf16 v[38:41], v[182:185], v[174:177], v[38:41]
	v_mfma_f32_16x16x32_bf16 v[34:37], v[190:193], v[174:177], v[34:37]
	s_setprio 0
	s_barrier
	ds_read_b128 v[146:149], v214 offset:49152
	ds_read_b128 v[150:153], v214 offset:50176
	ds_read_b128 v[154:157], v214 offset:51200
	ds_read_b128 v[158:161], v214 offset:52224
	ds_read_b128 v[162:165], v214 offset:53248
	ds_read_b128 v[166:169], v214 offset:54272
	ds_read_b128 v[170:173], v214 offset:55296
	ds_read_b128 v[174:177], v214 offset:56320
	s_add_i32 s0, s0, s5
	v_lshl_add_u64 v[204:205], v[200:201], 0, s[38:39]
	s_mov_b32 m0, s0
	s_nop 0
	global_load_lds_dwordx4 v[204:205], off
	v_lshl_add_u64 v[204:205], v[200:201], 0, s[40:41]
	s_add_i32 m0, s0, 0x2000
	s_nop 0
	global_load_lds_dwordx4 v[204:205], off
	s_add_i32 s0, s1, s5
	v_lshl_add_u64 v[250:251], v[200:201], 0, s[42:43]
	s_mov_b32 m0, s0
	s_nop 0
	global_load_lds_dwordx4 v[250:251], off
	v_lshl_add_u64 v[250:251], v[200:201], 0, s[44:45]
	s_add_i32 m0, s0, 0x2000
	s_nop 0
	global_load_lds_dwordx4 v[250:251], off
	s_mov_b32 m0, s65
	v_lshl_add_u64 v[204:205], v[202:203], 0, s[38:39]
	global_load_lds_dwordx4 v[204:205], off
	v_lshl_add_u64 v[202:203], v[202:203], 0, s[40:41]
	s_mov_b32 m0, s66
	s_nop 0
	global_load_lds_dwordx4 v[202:203], off
	s_waitcnt vmcnt(8)
	s_waitcnt lgkmcnt(0)
	s_barrier
	s_setprio 1
	v_mfma_f32_16x16x32_bf16 v[94:97], v[130:133], v[146:149], v[94:97]
	v_mfma_f32_16x16x32_bf16 v[90:93], v[138:141], v[146:149], v[90:93]
	v_mfma_f32_16x16x32_bf16 v[86:89], v[130:133], v[154:157], v[86:89]
	v_mfma_f32_16x16x32_bf16 v[82:85], v[138:141], v[154:157], v[82:85]
	v_mfma_f32_16x16x32_bf16 v[78:81], v[130:133], v[162:165], v[78:81]
	v_mfma_f32_16x16x32_bf16 v[74:77], v[138:141], v[162:165], v[74:77]
	v_mfma_f32_16x16x32_bf16 v[70:73], v[130:133], v[170:173], v[70:73]
	v_mfma_f32_16x16x32_bf16 v[66:69], v[138:141], v[170:173], v[66:69]
	v_mfma_f32_16x16x32_bf16 v[94:97], v[134:137], v[150:153], v[94:97]
	v_mfma_f32_16x16x32_bf16 v[90:93], v[142:145], v[150:153], v[90:93]
	v_mfma_f32_16x16x32_bf16 v[86:89], v[134:137], v[158:161], v[86:89]
	v_mfma_f32_16x16x32_bf16 v[82:85], v[142:145], v[158:161], v[82:85]
	v_mfma_f32_16x16x32_bf16 v[78:81], v[134:137], v[166:169], v[78:81]
	v_mfma_f32_16x16x32_bf16 v[74:77], v[142:145], v[166:169], v[74:77]
	v_mfma_f32_16x16x32_bf16 v[70:73], v[134:137], v[174:177], v[70:73]
	v_mfma_f32_16x16x32_bf16 v[66:69], v[142:145], v[174:177], v[66:69]
	v_mfma_f32_16x16x32_bf16 v[30:33], v[178:181], v[146:149], v[30:33]
	v_mfma_f32_16x16x32_bf16 v[26:29], v[186:189], v[146:149], v[26:29]
	v_mfma_f32_16x16x32_bf16 v[22:25], v[178:181], v[154:157], v[22:25]
	v_mfma_f32_16x16x32_bf16 v[18:21], v[186:189], v[154:157], v[18:21]
	v_mfma_f32_16x16x32_bf16 v[14:17], v[178:181], v[162:165], v[14:17]
	v_mfma_f32_16x16x32_bf16 v[10:13], v[186:189], v[162:165], v[10:13]
	v_mfma_f32_16x16x32_bf16 v[6:9], v[178:181], v[170:173], v[6:9]
	v_mfma_f32_16x16x32_bf16 v[2:5], v[186:189], v[170:173], v[2:5]
	v_mfma_f32_16x16x32_bf16 v[30:33], v[182:185], v[150:153], v[30:33]
	v_mfma_f32_16x16x32_bf16 v[26:29], v[190:193], v[150:153], v[26:29]
	v_mfma_f32_16x16x32_bf16 v[22:25], v[182:185], v[158:161], v[22:25]
	v_mfma_f32_16x16x32_bf16 v[18:21], v[190:193], v[158:161], v[18:21]
	v_mfma_f32_16x16x32_bf16 v[14:17], v[182:185], v[166:169], v[14:17]
	v_mfma_f32_16x16x32_bf16 v[10:13], v[190:193], v[166:169], v[10:13]
	v_mfma_f32_16x16x32_bf16 v[6:9], v[182:185], v[174:177], v[6:9]
	v_mfma_f32_16x16x32_bf16 v[2:5], v[190:193], v[174:177], v[2:5]
	s_setprio 0
	s_add_i32 s86, s86, 2
	s_add_u32 s62, s62, 0x100
	s_addc_u32 s63, s63, 0
	s_add_u32 s60, s60, 0x100
	s_addc_u32 s61, s61, 0
	s_cmp_gt_u32 s86, 13
	s_barrier
	s_cbranch_scc0 .LBB0_1706
	s_and_b64 vcc, exec, s[46:47]
	s_cbranch_vccz .LBB0_1709
	s_barrier
